# branch A: b_s loads hoisted to group top, counted vmcnt waits instead of vmcnt(0) drains
# speedup vs baseline: 1.0289x; 1.0001x over previous
; __device__ __forceinline__ u32x4 pack8(const f32x4 a, const f32x4 b) { u32x4 w; w.x = cvt_pk_bf16(a[0], a[1]); w.y = cvt_pk_bf16(a[2], a[3]); w.z = cvt_pk_bf16(b[0], b[1]); w.w = cvt_pk_bf16(b[2], b[3]); return w; }
; #define LAS __attribute__((address_space(3)))
; #define BA_LOAD_UG(g_) do { _Pragma("unroll") for (int i = 0; i < 4; ++i) { const int p = tid + 512 * i, t = p >> 4, dc = p & 15; ugp[i] = *(const u32x4*)(UGQ + (t0 + t) * 2048 + (g_) * 128 + dc * 8); } } while (0)
; #define BA_LOAD_WS(g_) do { _Pragma("unroll") for (int j = 0; j < 2; ++j) { const int tb = 2 * tbp + j; const bf16* wrow = WsB + ((size_t)(g_) * 128 + 32 * tb + r32) * 128 + hi * 8; \
;         _Pragma("unroll") for (int ks = 0; ks < 8; ++ks) if (ks < 2 * (tb + 1)) wf[j][ks] = *(const bf16x8*)(wrow + ks * 16); } } while (0)
;     ...
;         if (g + 1 < 8) BA_LOAD_WS(g + 1);
; #pragma unroll
;         for (int j = 0; j < 2; ++j) {
;             const int tb = 2 * tbp + j, t = 32 * tb + r32;
;             const float bias = b_s[g * 128 + t];
;             LAS float* ot = (LAS float*)(lds + BA_OT) + t * 132 + 32 * dblk + 4 * hi;
; #pragma unroll
;             for (int g4 = 0; g4 < 4; ++g4) *(LAS f32x4*)(ot + 8 * g4) = (f32x4){acc[j][4 * g4] + bias, acc[j][4 * g4 + 1] + bias, acc[j][4 * g4 + 2] + bias, acc[j][4 * g4 + 3] + bias};
;         }
;         __syncthreads();
; #pragma unroll
;         for (int i = 0; i < 4; ++i) {
;             const int p = tid + 512 * i, t = p >> 4, dc = p & 15;
;             const LAS float* ot = (const LAS float*)(lds + BA_OT) + t * 132 + dc * 8;
;             const f32x4 m0 = *(const LAS f32x4*)ot, m1 = *(const LAS f32x4*)(ot + 4);
;             bf16* up = UGQ + (t0 + t) * 2048 + g * 128 + dc * 8;
;             f32x4 u0, u1; pg8::unpack8(ugp[i], u0, u1);
;             if (!dry) *(u32x4*)up = pg8::pack8(u0 * m0, u1 * m1);
;         }
;         if (g + 1 < 8) BA_LOAD_UG(g + 1);
.LBB0_509:
	s_add_u32 s22, s22, 0x8000
	s_mov_b64 s[0:1], 0x200
	s_addc_u32 s23, s23, 0
	v_add_u32_e32 v176, 0x200, v176
	v_readfirstlane_b32 s98, v232
	s_bitcmp1_b32 s98, 8
	s_cbranch_scc1 .Lba_w3_hi
	s_waitcnt vmcnt(10)
	s_branch .Lba_w3_done
.Lba_w3_hi:
	s_waitcnt vmcnt(18)
.Lba_w3_done:
	s_cmp_eq_u32 s22, 0x38000
	v_pk_add_f32 v[0:1], v[0:1], v[182:183] op_sel_hi:[1,0]
	v_pk_add_f32 v[2:3], v[2:3], v[182:183] op_sel_hi:[1,0]
	ds_write_b128 v167, v[0:3] offset:44032
	v_pk_add_f32 v[0:1], v[4:5], v[182:183] op_sel_hi:[1,0]
	v_pk_add_f32 v[2:3], v[6:7], v[182:183] op_sel_hi:[1,0]
	ds_write_b128 v167, v[0:3] offset:44064
	v_pk_add_f32 v[0:1], v[8:9], v[182:183] op_sel_hi:[1,0]
	v_pk_add_f32 v[2:3], v[10:11], v[182:183] op_sel_hi:[1,0]
	ds_write_b128 v167, v[0:3] offset:44096
	v_pk_add_f32 v[0:1], v[12:13], v[182:183] op_sel_hi:[1,0]
	v_pk_add_f32 v[2:3], v[14:15], v[182:183] op_sel_hi:[1,0]
	ds_write_b128 v167, v[0:3] offset:44128
	v_lshlrev_b32_e32 v10, 16, v60
	v_and_b32_e32 v11, 0xffff0000, v60
	v_lshlrev_b32_e32 v12, 16, v61
	v_and_b32_e32 v13, 0xffff0000, v61
	v_lshlrev_b32_e32 v14, 16, v62
	v_and_b32_e32 v15, 0xffff0000, v62
	v_lshl_add_u64 v[144:145], v[144:145], 0, s[0:1]
	s_mov_b64 s[0:1], 0x100
	v_lshl_add_u64 v[154:155], v[154:155], 0, s[0:1]
	v_lshl_add_u64 v[156:157], v[156:157], 0, s[0:1]
	v_lshl_add_u64 v[158:159], v[158:159], 0, s[0:1]
	v_lshl_add_u64 v[160:161], v[160:161], 0, s[0:1]
	v_pk_add_f32 v[0:1], v[16:17], v[184:185] op_sel_hi:[1,0]
	v_pk_add_f32 v[2:3], v[18:19], v[184:185] op_sel_hi:[1,0]
	ds_write_b128 v167, v[0:3] offset:60928
	v_pk_add_f32 v[0:1], v[20:21], v[184:185] op_sel_hi:[1,0]
	v_pk_add_f32 v[2:3], v[22:23], v[184:185] op_sel_hi:[1,0]
	ds_write_b128 v167, v[0:3] offset:60960
	v_pk_add_f32 v[0:1], v[24:25], v[184:185] op_sel_hi:[1,0]
	v_pk_add_f32 v[2:3], v[26:27], v[184:185] op_sel_hi:[1,0]
	ds_write_b128 v167, v[0:3] offset:60992
	v_pk_add_f32 v[0:1], v[28:29], v[184:185] op_sel_hi:[1,0]
	v_pk_add_f32 v[2:3], v[30:31], v[184:185] op_sel_hi:[1,0]
	ds_write_b128 v167, v[0:3] offset:61024
	s_waitcnt lgkmcnt(0)
	s_barrier
	ds_read_b128 v[2:5], v166 offset:44032
	ds_read_b128 v[6:9], v166 offset:44048
	v_lshlrev_b32_e32 v16, 16, v63
	v_and_b32_e32 v17, 0xffff0000, v63
	v_lshl_add_u64 v[0:1], v[152:153], 0, v[64:65]
	s_waitcnt lgkmcnt(1)
	v_pk_mul_f32 v[4:5], v[4:5], v[12:13]
	v_pk_mul_f32 v[2:3], v[2:3], v[10:11]
	s_waitcnt lgkmcnt(0)
	v_pk_mul_f32 v[8:9], v[8:9], v[16:17]
	v_pk_mul_f32 v[6:7], v[6:7], v[14:15]
	v_cvt_pk_bf16_f32 v2, v2, v3
	v_cvt_pk_bf16_f32 v3, v4, v5
	v_cvt_pk_bf16_f32 v4, v6, v7
	v_cvt_pk_bf16_f32 v5, v8, v9
	global_store_dwordx4 v[0:1], v[2:5], off offset:-256
	ds_read_b128 v[4:7], v165 offset:44032
	ds_read_b128 v[8:11], v165 offset:44048
	v_lshlrev_b32_e32 v12, 16, v44
	v_and_b32_e32 v13, 0xffff0000, v44
	v_lshlrev_b32_e32 v14, 16, v45
	v_and_b32_e32 v15, 0xffff0000, v45
	v_lshlrev_b32_e32 v16, 16, v46
	v_and_b32_e32 v17, 0xffff0000, v46
	v_lshlrev_b32_e32 v18, 16, v47
	v_and_b32_e32 v19, 0xffff0000, v47
	s_waitcnt lgkmcnt(1)
	v_pk_mul_f32 v[6:7], v[6:7], v[14:15]
	v_pk_mul_f32 v[4:5], v[4:5], v[12:13]
	s_waitcnt lgkmcnt(0)
	v_pk_mul_f32 v[10:11], v[10:11], v[18:19]
	v_pk_mul_f32 v[8:9], v[8:9], v[16:17]
	v_lshl_add_u64 v[2:3], v[150:151], 0, v[64:65]
	v_cvt_pk_bf16_f32 v4, v4, v5
	v_cvt_pk_bf16_f32 v5, v6, v7
	v_cvt_pk_bf16_f32 v6, v8, v9
	v_cvt_pk_bf16_f32 v7, v10, v11
	global_store_dwordx4 v[2:3], v[4:7], off offset:-256
	ds_read_b128 v[6:9], v164 offset:44032
	ds_read_b128 v[10:13], v164 offset:44048
	v_lshlrev_b32_e32 v14, 16, v36
	v_and_b32_e32 v15, 0xffff0000, v36
	v_lshlrev_b32_e32 v16, 16, v37
	v_and_b32_e32 v17, 0xffff0000, v37
	v_lshlrev_b32_e32 v18, 16, v38
	v_and_b32_e32 v19, 0xffff0000, v38
	v_lshlrev_b32_e32 v20, 16, v39
	v_and_b32_e32 v21, 0xffff0000, v39
	s_waitcnt lgkmcnt(1)
	v_pk_mul_f32 v[8:9], v[8:9], v[16:17]
	v_pk_mul_f32 v[6:7], v[6:7], v[14:15]
	s_waitcnt lgkmcnt(0)
	v_pk_mul_f32 v[12:13], v[12:13], v[20:21]
	v_pk_mul_f32 v[10:11], v[10:11], v[18:19]
	v_lshl_add_u64 v[4:5], v[148:149], 0, v[64:65]
	v_cvt_pk_bf16_f32 v6, v6, v7
	v_cvt_pk_bf16_f32 v7, v8, v9
	v_cvt_pk_bf16_f32 v8, v10, v11
	v_cvt_pk_bf16_f32 v9, v12, v13
	global_store_dwordx4 v[4:5], v[6:9], off offset:-256
	ds_read_b128 v[6:9], v141 offset:44032
	ds_read_b128 v[10:13], v141 offset:44048
	v_lshlrev_b32_e32 v14, 16, v32
	v_and_b32_e32 v15, 0xffff0000, v32
	v_lshlrev_b32_e32 v16, 16, v33
	v_and_b32_e32 v17, 0xffff0000, v33
	v_lshlrev_b32_e32 v18, 16, v34
	v_and_b32_e32 v19, 0xffff0000, v34
	v_lshlrev_b32_e32 v20, 16, v35
	v_and_b32_e32 v21, 0xffff0000, v35
	s_waitcnt lgkmcnt(1)
	v_pk_mul_f32 v[8:9], v[8:9], v[16:17]
	v_pk_mul_f32 v[6:7], v[6:7], v[14:15]
	s_waitcnt lgkmcnt(0)
	v_pk_mul_f32 v[12:13], v[12:13], v[20:21]
	v_pk_mul_f32 v[10:11], v[10:11], v[18:19]
	v_lshl_add_u64 v[22:23], v[146:147], 0, v[64:65]
	v_cvt_pk_bf16_f32 v6, v6, v7
	v_cvt_pk_bf16_f32 v7, v8, v9
	v_cvt_pk_bf16_f32 v8, v10, v11
	v_cvt_pk_bf16_f32 v9, v12, v13
	global_store_dwordx4 v[22:23], v[6:9], off offset:-256
	global_load_dwordx4 v[60:63], v[0:1], off
	global_load_dwordx4 v[44:47], v[2:3], off
	global_load_dwordx4 v[36:39], v[4:5], off
	global_load_dwordx4 v[32:35], v[22:23], off
	v_lshl_add_u64 v[146:147], v[146:147], 0, s[0:1]
	v_lshl_add_u64 v[148:149], v[148:149], 0, s[0:1]
	v_lshl_add_u64 v[150:151], v[150:151], 0, s[0:1]
	v_lshl_add_u64 v[152:153], v[152:153], 0, s[0:1]
	s_cbranch_scc1 .LBB0_574
; __device__ __forceinline__ u32x4 pack8(const f32x4 a, const f32x4 b) { u32x4 w; w.x = cvt_pk_bf16(a[0], a[1]); w.y = cvt_pk_bf16(a[2], a[3]); w.z = cvt_pk_bf16(b[0], b[1]); w.w = cvt_pk_bf16(b[2], b[3]); return w; }
; #define LAS __attribute__((address_space(3)))
;     ...
;     for (int g = 0; g < 8; ++g) {
;         const f32x4 ga = *(const LAS f32x4*)(gbl + g * 128 + (tid & 15) * 8), gb2 = *(const LAS f32x4*)(gbl + g * 128 + (tid & 15) * 8 + 4);
;         const f32x4 ba = *(const LAS f32x4*)(gbl + 1024 + g * 128 + (tid & 15) * 8), bb2 = *(const LAS f32x4*)(gbl + 1024 + g * 128 + (tid & 15) * 8 + 4);
; #pragma unroll
;         for (int i = 0; i < 4; ++i) {
;             const int p = tid + 512 * i, s = p >> 4, dc = p & 15;
;             f32x4 v0, v1; pg8::unpack8(vpc[i], v0, v1);
;             const float mean = stat[s * 2], rstd = stat[s * 2 + 1];
;             v0 = (v0 - mean) * rstd * ga + ba; v1 = (v1 - mean) * rstd * gb2 + bb2;
;             const u32x4 w = pg8::pack8(v0, v1);
;             LAS unsigned short* dst = (LAS unsigned short*)(lds + BA_VNT) + dc * 136 + s;
;             dst[0 * 16 * 136] = (unsigned short)(w.x & 0xffffu); dst[1 * 16 * 136] = (unsigned short)(w.x >> 16); dst[2 * 16 * 136] = (unsigned short)(w.y & 0xffffu); dst[3 * 16 * 136] = (unsigned short)(w.y >> 16);
;             dst[4 * 16 * 136] = (unsigned short)(w.z & 0xffffu); dst[5 * 16 * 136] = (unsigned short)(w.z >> 16); dst[6 * 16 * 136] = (unsigned short)(w.w & 0xffffu); dst[7 * 16 * 136] = (unsigned short)(w.w >> 16);
;         }
;         if (g + 1 < 8) {
; #pragma unroll
;             for (int i = 0; i < 4; ++i) { const int p = tid + 512 * i, s = p >> 4, dc = p & 15; vpc[i] = *(const u32x4*)(Vb + (t0 + s) * 1024 + (g + 1) * 128 + dc * 8); }
;         }
;         __syncthreads();
.LBB0_510:
	global_load_dword v182, v[144:145], off offset:-128
	global_load_dword v184, v[144:145], off
	s_waitcnt vmcnt(19)
	ds_read_b128 v[8:11], v176
	ds_read_b128 v[0:3], v176 offset:16
	ds_read_b128 v[12:15], v176 offset:4096
	ds_read_b128 v[4:7], v176 offset:4112
	ds_read_b64 v[16:17], v177
	v_lshlrev_b32_e32 v20, 16, v126
	v_and_b32_e32 v21, 0xffff0000, v126
	v_lshlrev_b32_e32 v18, 16, v127
	v_and_b32_e32 v19, 0xffff0000, v127
	v_lshlrev_b32_e32 v24, 16, v128
	v_and_b32_e32 v25, 0xffff0000, v128
	v_lshlrev_b32_e32 v22, 16, v129
	v_and_b32_e32 v23, 0xffff0000, v129
	s_waitcnt lgkmcnt(0)
	v_sub_f32_e32 v21, v21, v16
	v_sub_f32_e32 v20, v20, v16
	v_sub_f32_e32 v19, v19, v16
	v_sub_f32_e32 v18, v18, v16
	v_pk_mul_f32 v[20:21], v[16:17], v[20:21] op_sel:[1,0]
	v_sub_f32_e32 v23, v23, v16
	v_sub_f32_e32 v22, v22, v16
	v_sub_f32_e32 v25, v25, v16
	v_sub_f32_e32 v24, v24, v16
	v_pk_mul_f32 v[18:19], v[16:17], v[18:19] op_sel:[1,0]
	v_pk_fma_f32 v[20:21], v[8:9], v[20:21], v[12:13]
	v_pk_mul_f32 v[24:25], v[16:17], v[24:25] op_sel:[1,0]
	v_pk_mul_f32 v[16:17], v[16:17], v[22:23] op_sel:[1,0]
	v_pk_fma_f32 v[18:19], v[10:11], v[18:19], v[14:15]
	v_pk_fma_f32 v[16:17], v[2:3], v[16:17], v[6:7]
	v_pk_fma_f32 v[22:23], v[0:1], v[24:25], v[4:5]
	v_cvt_pk_bf16_f32 v20, v20, v21
	v_cvt_pk_bf16_f32 v18, v18, v19
	v_cvt_pk_bf16_f32 v19, v22, v23
	v_cvt_pk_bf16_f32 v16, v16, v17
	ds_write_b16 v174, v20 offset:9216
	ds_write_b16_d16_hi v174, v20 offset:13568
	ds_write_b16 v174, v18 offset:17920
	ds_write_b16_d16_hi v174, v18 offset:22272
	ds_write_b16 v174, v19 offset:26624
	ds_write_b16_d16_hi v174, v19 offset:30976
	ds_write_b16 v174, v16 offset:35328
	ds_write_b16_d16_hi v174, v16 offset:39680
	ds_read_b64 v[16:17], v173
	s_waitcnt vmcnt(18)
	v_lshlrev_b32_e32 v20, 16, v122
	v_and_b32_e32 v21, 0xffff0000, v122
	v_lshlrev_b32_e32 v18, 16, v123
	v_and_b32_e32 v19, 0xffff0000, v123
	v_lshlrev_b32_e32 v24, 16, v124
	v_and_b32_e32 v25, 0xffff0000, v124
	v_lshlrev_b32_e32 v22, 16, v125
	v_and_b32_e32 v23, 0xffff0000, v125
	s_waitcnt lgkmcnt(0)
	v_sub_f32_e32 v21, v21, v16
	v_sub_f32_e32 v20, v20, v16
	v_sub_f32_e32 v19, v19, v16
	v_sub_f32_e32 v18, v18, v16
	v_pk_mul_f32 v[20:21], v[16:17], v[20:21] op_sel:[1,0]
	v_sub_f32_e32 v23, v23, v16
	v_sub_f32_e32 v22, v22, v16
	v_sub_f32_e32 v25, v25, v16
	v_sub_f32_e32 v24, v24, v16
	v_pk_mul_f32 v[18:19], v[16:17], v[18:19] op_sel:[1,0]
	v_pk_fma_f32 v[20:21], v[8:9], v[20:21], v[12:13]
	v_pk_mul_f32 v[24:25], v[16:17], v[24:25] op_sel:[1,0]
	v_pk_mul_f32 v[16:17], v[16:17], v[22:23] op_sel:[1,0]
	v_pk_fma_f32 v[18:19], v[10:11], v[18:19], v[14:15]
	v_pk_fma_f32 v[16:17], v[2:3], v[16:17], v[6:7]
	v_pk_fma_f32 v[22:23], v[0:1], v[24:25], v[4:5]
	v_cvt_pk_bf16_f32 v20, v20, v21
	v_cvt_pk_bf16_f32 v18, v18, v19
	v_cvt_pk_bf16_f32 v19, v22, v23
	v_cvt_pk_bf16_f32 v16, v16, v17
	ds_write_b16 v172, v20 offset:9216
	ds_write_b16_d16_hi v172, v20 offset:13568
	ds_write_b16 v172, v18 offset:17920
	ds_write_b16_d16_hi v172, v18 offset:22272
	ds_write_b16 v172, v19 offset:26624
	ds_write_b16_d16_hi v172, v19 offset:30976
	ds_write_b16 v172, v16 offset:35328
	ds_write_b16_d16_hi v172, v16 offset:39680
	ds_read_b64 v[16:17], v171
	s_waitcnt vmcnt(13)
	v_lshlrev_b32_e32 v20, 16, v118
	v_and_b32_e32 v21, 0xffff0000, v118
	v_lshlrev_b32_e32 v18, 16, v119
	v_and_b32_e32 v19, 0xffff0000, v119
	v_lshlrev_b32_e32 v24, 16, v120
	v_and_b32_e32 v25, 0xffff0000, v120
	v_lshlrev_b32_e32 v22, 16, v121
	v_and_b32_e32 v23, 0xffff0000, v121
	s_waitcnt lgkmcnt(0)
	v_sub_f32_e32 v21, v21, v16
	v_sub_f32_e32 v20, v20, v16
	v_sub_f32_e32 v19, v19, v16
	v_sub_f32_e32 v18, v18, v16
	v_pk_mul_f32 v[20:21], v[16:17], v[20:21] op_sel:[1,0]
	v_sub_f32_e32 v23, v23, v16
	v_sub_f32_e32 v22, v22, v16
	v_sub_f32_e32 v25, v25, v16
	v_sub_f32_e32 v24, v24, v16
	v_pk_mul_f32 v[18:19], v[16:17], v[18:19] op_sel:[1,0]
	v_pk_fma_f32 v[20:21], v[8:9], v[20:21], v[12:13]
	v_pk_mul_f32 v[24:25], v[16:17], v[24:25] op_sel:[1,0]
	v_pk_mul_f32 v[16:17], v[16:17], v[22:23] op_sel:[1,0]
	v_pk_fma_f32 v[18:19], v[10:11], v[18:19], v[14:15]
	v_pk_fma_f32 v[16:17], v[2:3], v[16:17], v[6:7]
	v_pk_fma_f32 v[22:23], v[0:1], v[24:25], v[4:5]
	v_cvt_pk_bf16_f32 v20, v20, v21
	v_cvt_pk_bf16_f32 v18, v18, v19
	v_cvt_pk_bf16_f32 v19, v22, v23
	v_cvt_pk_bf16_f32 v16, v16, v17
	ds_write_b16 v170, v20 offset:9216
	ds_write_b16_d16_hi v170, v20 offset:13568
	ds_write_b16 v170, v18 offset:17920
	ds_write_b16_d16_hi v170, v18 offset:22272
	ds_write_b16 v170, v19 offset:26624
	ds_write_b16_d16_hi v170, v19 offset:30976
	ds_write_b16 v170, v16 offset:35328
	ds_write_b16_d16_hi v170, v16 offset:39680
	ds_read_b64 v[16:17], v169
	s_waitcnt vmcnt(12)
	v_lshlrev_b32_e32 v20, 16, v114
	v_and_b32_e32 v21, 0xffff0000, v114
	v_lshlrev_b32_e32 v18, 16, v115
	v_and_b32_e32 v19, 0xffff0000, v115
	s_waitcnt lgkmcnt(0)
	v_sub_f32_e32 v19, v19, v16
	v_sub_f32_e32 v18, v18, v16
	v_sub_f32_e32 v21, v21, v16
	v_sub_f32_e32 v20, v20, v16
	v_lshlrev_b32_e32 v22, 16, v116
	v_and_b32_e32 v23, 0xffff0000, v116
	v_lshlrev_b32_e32 v24, 16, v117
	v_and_b32_e32 v25, 0xffff0000, v117
	v_pk_mul_f32 v[20:21], v[16:17], v[20:21] op_sel:[1,0]
	v_pk_mul_f32 v[18:19], v[16:17], v[18:19] op_sel:[1,0]
	v_pk_fma_f32 v[8:9], v[8:9], v[20:21], v[12:13]
	v_pk_fma_f32 v[10:11], v[10:11], v[18:19], v[14:15]
	v_sub_f32_e32 v13, v25, v16
	v_sub_f32_e32 v12, v24, v16
	v_sub_f32_e32 v15, v23, v16
	v_sub_f32_e32 v14, v22, v16
	v_pk_mul_f32 v[14:15], v[16:17], v[14:15] op_sel:[1,0]
	v_pk_mul_f32 v[12:13], v[16:17], v[12:13] op_sel:[1,0]
	v_pk_fma_f32 v[0:1], v[0:1], v[14:15], v[4:5]
	v_pk_fma_f32 v[2:3], v[2:3], v[12:13], v[6:7]
	v_cvt_pk_bf16_f32 v4, v8, v9
	v_cvt_pk_bf16_f32 v0, v0, v1
	v_cvt_pk_bf16_f32 v1, v2, v3
	v_cvt_pk_bf16_f32 v5, v10, v11
	ds_write_b16 v168, v4 offset:9216
	ds_write_b16_d16_hi v168, v4 offset:13568
	ds_write_b16 v168, v5 offset:17920
	ds_write_b16_d16_hi v168, v5 offset:22272
	ds_write_b16 v168, v0 offset:26624
	ds_write_b16_d16_hi v168, v0 offset:30976
	ds_write_b16 v168, v1 offset:35328
	ds_write_b16_d16_hi v168, v1 offset:39680
	v_lshl_add_u64 v[0:1], v[156:157], 0, v[64:65]
	global_load_dwordx4 v[126:129], v[0:1], off
	v_lshl_add_u64 v[0:1], v[158:159], 0, v[64:65]
	global_load_dwordx4 v[122:125], v[0:1], off
	v_lshl_add_u64 v[0:1], v[160:161], 0, v[64:65]
	global_load_dwordx4 v[118:121], v[0:1], off
	v_lshl_add_u64 v[0:1], v[154:155], 0, v[64:65]
	global_load_dwordx4 v[114:117], v[0:1], off
	s_and_b64 vcc, exec, s[38:39]
	v_mov_b32_e32 v0, 0
	v_mov_b32_e32 v1, 0
	v_mov_b32_e32 v2, 0
	v_mov_b32_e32 v3, 0
	v_mov_b32_e32 v4, 0
	v_mov_b32_e32 v5, 0
	v_mov_b32_e32 v6, 0
	v_mov_b32_e32 v7, 0
	v_mov_b32_e32 v8, 0
	v_mov_b32_e32 v9, 0
	v_mov_b32_e32 v10, 0
	v_mov_b32_e32 v11, 0
	v_mov_b32_e32 v12, 0
	v_mov_b32_e32 v13, 0
	v_mov_b32_e32 v14, 0
	v_mov_b32_e32 v15, 0
	s_waitcnt vmcnt(10)
	s_waitcnt lgkmcnt(0)
	s_barrier
; #define LAS __attribute__((address_space(3)))
;     ...
;         const int d = 32 * dblk + r32;
;         const LAS unsigned char* ab = lds + BA_VNT + ((d & 7) * 16 + (d >> 3)) * 272 + hi * 16;
;         f32x16 acc[2];
; #pragma unroll
;         for (int j = 0; j < 2; ++j) {
;             const int tb = 2 * tbp + j;
; #pragma unroll
;             for (int r = 0; r < 16; ++r) acc[j][r] = 0.f;
; #pragma unroll
;             for (int ks = 0; ks < 8; ++ks) if (ks < 2 * (tb + 1)) {
;                 const bf16x8 af = *(const LAS bf16x8*)(ab + ks * 32);
;                 acc[j] = __builtin_amdgcn_mfma_f32_32x32x16_bf16(af, wf[j][ks], acc[j], 0, 0, 0);
;             }
	s_cbranch_vccnz .LBB0_512
	v_add_u32_e32 v0, v139, v140
	ds_read_b128 v[0:3], v0 offset:9216
	s_waitcnt lgkmcnt(0)
	v_mfma_f32_32x32x16_bf16 v[0:15], v[0:3], v[110:113], 0

; __device__ __forceinline__ u32x4 pack8(const f32x4 a, const f32x4 b) { u32x4 w; w.x = cvt_pk_bf16(a[0], a[1]); w.y = cvt_pk_bf16(a[2], a[3]); w.z = cvt_pk_bf16(b[0], b[1]); w.w = cvt_pk_bf16(b[2], b[3]); return w; }
;     ...
;     for (int g = 0; g < 8; ++g) {
;         const f32x4 ga = *(const LAS f32x4*)(gbl + g * 128 + (tid & 15) * 8), gb2 = *(const LAS f32x4*)(gbl + g * 128 + (tid & 15) * 8 + 4);
;         const f32x4 ba = *(const LAS f32x4*)(gbl + 1024 + g * 128 + (tid & 15) * 8), bb2 = *(const LAS f32x4*)(gbl + 1024 + g * 128 + (tid & 15) * 8 + 4);
; #pragma unroll
;         for (int i = 0; i < 4; ++i) {
;             const int p = tid + 512 * i, s = p >> 4, dc = p & 15;
;             f32x4 v0, v1; pg8::unpack8(vpc[i], v0, v1);
;             const float mean = stat[s * 2], rstd = stat[s * 2 + 1];
;             v0 = (v0 - mean) * rstd * ga + ba; v1 = (v1 - mean) * rstd * gb2 + bb2;
;             const u32x4 w = pg8::pack8(v0, v1);
;             LAS unsigned short* dst = (LAS unsigned short*)(lds + BA_VNT) + dc * 136 + s;
;             dst[0 * 16 * 136] = (unsigned short)(w.x & 0xffffu); dst[1 * 16 * 136] = (unsigned short)(w.x >> 16); dst[2 * 16 * 136] = (unsigned short)(w.y & 0xffffu); dst[3 * 16 * 136] = (unsigned short)(w.y >> 16);
;             dst[4 * 16 * 136] = (unsigned short)(w.z & 0xffffu); dst[5 * 16 * 136] = (unsigned short)(w.z >> 16); dst[6 * 16 * 136] = (unsigned short)(w.w & 0xffffu); dst[7 * 16 * 136] = (unsigned short)(w.w >> 16);
;         }
;         if (g + 1 < 8) {
; #pragma unroll
;             for (int i = 0; i < 4; ++i) { const int p = tid + 512 * i, s = p >> 4, dc = p & 15; vpc[i] = *(const u32x4*)(Vb + (t0 + s) * 1024 + (g + 1) * 128 + dc * 8); }
;         }
;         __syncthreads();
;         const int d = 32 * dblk + r32;
;         const LAS unsigned char* ab = lds + BA_VNT + ((d & 7) * 16 + (d >> 3)) * 272 + hi * 16;
;         f32x16 acc[2];
; #pragma unroll
;         for (int j = 0; j < 2; ++j) {
;             const int tb = 2 * tbp + j;
; #pragma unroll
;             for (int r = 0; r < 16; ++r) acc[j][r] = 0.f;
; #pragma unroll
;             for (int ks = 0; ks < 8; ++ks) if (ks < 2 * (tb + 1)) {
;                 const bf16x8 af = *(const LAS bf16x8*)(ab + ks * 32);
;                 acc[j] = __builtin_amdgcn_mfma_f32_32x32x16_bf16(af, wf[j][ks], acc[j], 0, 0, 0);
;             }
.LBB0_574:
	s_waitcnt vmcnt(8)
	ds_read_b128 v[8:11], v175 offset:4608
	ds_read_b128 v[0:3], v175 offset:4624
	ds_read_b128 v[12:15], v175 offset:8704
	ds_read_b128 v[4:7], v175 offset:8720
	ds_read_b64 v[16:17], v177
	v_lshlrev_b32_e32 v20, 16, v126
	v_and_b32_e32 v21, 0xffff0000, v126
	v_lshlrev_b32_e32 v18, 16, v127
	v_and_b32_e32 v19, 0xffff0000, v127
	v_lshlrev_b32_e32 v24, 16, v128
	v_and_b32_e32 v25, 0xffff0000, v128
	v_lshlrev_b32_e32 v22, 16, v129
	v_and_b32_e32 v23, 0xffff0000, v129
	s_waitcnt lgkmcnt(0)
	v_sub_f32_e32 v21, v21, v16
	v_sub_f32_e32 v20, v20, v16
	v_sub_f32_e32 v19, v19, v16
	v_sub_f32_e32 v18, v18, v16
	v_pk_mul_f32 v[20:21], v[16:17], v[20:21] op_sel:[1,0]
	v_sub_f32_e32 v23, v23, v16
	v_sub_f32_e32 v22, v22, v16
	v_sub_f32_e32 v25, v25, v16
	v_sub_f32_e32 v24, v24, v16
	v_pk_mul_f32 v[18:19], v[16:17], v[18:19] op_sel:[1,0]
	v_pk_fma_f32 v[20:21], v[8:9], v[20:21], v[12:13]
	v_pk_mul_f32 v[24:25], v[16:17], v[24:25] op_sel:[1,0]
	v_pk_mul_f32 v[16:17], v[16:17], v[22:23] op_sel:[1,0]
	v_pk_fma_f32 v[18:19], v[10:11], v[18:19], v[14:15]
	v_pk_fma_f32 v[16:17], v[2:3], v[16:17], v[6:7]
	v_pk_fma_f32 v[22:23], v[0:1], v[24:25], v[4:5]
	v_cvt_pk_bf16_f32 v20, v20, v21
	v_cvt_pk_bf16_f32 v18, v18, v19
	v_cvt_pk_bf16_f32 v19, v22, v23
	v_cvt_pk_bf16_f32 v16, v16, v17
	ds_write_b16 v174, v20 offset:9216
	ds_write_b16_d16_hi v174, v20 offset:13568
	ds_write_b16 v174, v18 offset:17920
	ds_write_b16_d16_hi v174, v18 offset:22272
	ds_write_b16 v174, v19 offset:26624
	ds_write_b16_d16_hi v174, v19 offset:30976
	ds_write_b16 v174, v16 offset:35328
	ds_write_b16_d16_hi v174, v16 offset:39680
	ds_read_b64 v[16:17], v173
	v_lshlrev_b32_e32 v20, 16, v122
	v_and_b32_e32 v21, 0xffff0000, v122
	v_lshlrev_b32_e32 v18, 16, v123
	v_and_b32_e32 v19, 0xffff0000, v123
	v_lshlrev_b32_e32 v24, 16, v124
	v_and_b32_e32 v25, 0xffff0000, v124
	v_lshlrev_b32_e32 v22, 16, v125
	v_and_b32_e32 v23, 0xffff0000, v125
	s_waitcnt lgkmcnt(0)
	v_sub_f32_e32 v21, v21, v16
	v_sub_f32_e32 v20, v20, v16
	v_sub_f32_e32 v19, v19, v16
	v_sub_f32_e32 v18, v18, v16
	v_pk_mul_f32 v[20:21], v[16:17], v[20:21] op_sel:[1,0]
	v_sub_f32_e32 v23, v23, v16
	v_sub_f32_e32 v22, v22, v16
	v_sub_f32_e32 v25, v25, v16
	v_sub_f32_e32 v24, v24, v16
	v_pk_mul_f32 v[18:19], v[16:17], v[18:19] op_sel:[1,0]
	v_pk_fma_f32 v[20:21], v[8:9], v[20:21], v[12:13]
	v_pk_mul_f32 v[24:25], v[16:17], v[24:25] op_sel:[1,0]
	v_pk_mul_f32 v[16:17], v[16:17], v[22:23] op_sel:[1,0]
	v_pk_fma_f32 v[18:19], v[10:11], v[18:19], v[14:15]
	v_pk_fma_f32 v[16:17], v[2:3], v[16:17], v[6:7]
	v_pk_fma_f32 v[22:23], v[0:1], v[24:25], v[4:5]
	v_cvt_pk_bf16_f32 v20, v20, v21
	v_cvt_pk_bf16_f32 v18, v18, v19
	v_cvt_pk_bf16_f32 v19, v22, v23
	v_cvt_pk_bf16_f32 v16, v16, v17
	ds_write_b16 v172, v20 offset:9216
	ds_write_b16_d16_hi v172, v20 offset:13568
	ds_write_b16 v172, v18 offset:17920
	ds_write_b16_d16_hi v172, v18 offset:22272
	ds_write_b16 v172, v19 offset:26624
	ds_write_b16_d16_hi v172, v19 offset:30976
	ds_write_b16 v172, v16 offset:35328
	ds_write_b16_d16_hi v172, v16 offset:39680
	ds_read_b64 v[16:17], v171
	v_lshlrev_b32_e32 v20, 16, v118
	v_and_b32_e32 v21, 0xffff0000, v118
	v_lshlrev_b32_e32 v18, 16, v119
	v_and_b32_e32 v19, 0xffff0000, v119
	v_lshlrev_b32_e32 v24, 16, v120
	v_and_b32_e32 v25, 0xffff0000, v120
	v_lshlrev_b32_e32 v22, 16, v121
	v_and_b32_e32 v23, 0xffff0000, v121
	s_waitcnt lgkmcnt(0)
	v_sub_f32_e32 v21, v21, v16
	v_sub_f32_e32 v20, v20, v16
	v_sub_f32_e32 v19, v19, v16
	v_sub_f32_e32 v18, v18, v16
	v_pk_mul_f32 v[20:21], v[16:17], v[20:21] op_sel:[1,0]
	v_sub_f32_e32 v23, v23, v16
	v_sub_f32_e32 v22, v22, v16
	v_sub_f32_e32 v25, v25, v16
	v_sub_f32_e32 v24, v24, v16
	v_pk_mul_f32 v[18:19], v[16:17], v[18:19] op_sel:[1,0]
	v_pk_fma_f32 v[20:21], v[8:9], v[20:21], v[12:13]
	v_pk_mul_f32 v[24:25], v[16:17], v[24:25] op_sel:[1,0]
	v_pk_mul_f32 v[16:17], v[16:17], v[22:23] op_sel:[1,0]
	v_pk_fma_f32 v[18:19], v[10:11], v[18:19], v[14:15]
	v_pk_fma_f32 v[16:17], v[2:3], v[16:17], v[6:7]
	v_pk_fma_f32 v[22:23], v[0:1], v[24:25], v[4:5]
	v_cvt_pk_bf16_f32 v20, v20, v21
	v_cvt_pk_bf16_f32 v18, v18, v19
	v_cvt_pk_bf16_f32 v19, v22, v23
	v_cvt_pk_bf16_f32 v16, v16, v17
	ds_write_b16 v170, v20 offset:9216
	ds_write_b16_d16_hi v170, v20 offset:13568
	ds_write_b16 v170, v18 offset:17920
	ds_write_b16_d16_hi v170, v18 offset:22272
	ds_write_b16 v170, v19 offset:26624
	ds_write_b16_d16_hi v170, v19 offset:30976
	ds_write_b16 v170, v16 offset:35328
	ds_write_b16_d16_hi v170, v16 offset:39680
	ds_read_b64 v[16:17], v169
	v_lshlrev_b32_e32 v20, 16, v114
	v_and_b32_e32 v21, 0xffff0000, v114
	v_lshlrev_b32_e32 v18, 16, v115
	v_and_b32_e32 v19, 0xffff0000, v115
	s_waitcnt lgkmcnt(0)
	v_sub_f32_e32 v19, v19, v16
	v_sub_f32_e32 v18, v18, v16
	v_sub_f32_e32 v21, v21, v16
	v_sub_f32_e32 v20, v20, v16
	v_lshlrev_b32_e32 v22, 16, v116
	v_and_b32_e32 v23, 0xffff0000, v116
	v_lshlrev_b32_e32 v24, 16, v117
	v_and_b32_e32 v25, 0xffff0000, v117
	v_pk_mul_f32 v[20:21], v[16:17], v[20:21] op_sel:[1,0]
	v_pk_mul_f32 v[18:19], v[16:17], v[18:19] op_sel:[1,0]
	v_pk_fma_f32 v[8:9], v[8:9], v[20:21], v[12:13]
	v_pk_fma_f32 v[10:11], v[10:11], v[18:19], v[14:15]
	v_sub_f32_e32 v13, v25, v16
	v_sub_f32_e32 v12, v24, v16
	v_sub_f32_e32 v15, v23, v16
	v_sub_f32_e32 v14, v22, v16
	v_pk_mul_f32 v[14:15], v[16:17], v[14:15] op_sel:[1,0]
	v_pk_mul_f32 v[12:13], v[16:17], v[12:13] op_sel:[1,0]
	v_pk_fma_f32 v[0:1], v[0:1], v[14:15], v[4:5]
	v_pk_fma_f32 v[2:3], v[2:3], v[12:13], v[6:7]
	v_cvt_pk_bf16_f32 v4, v8, v9
	s_and_b64 vcc, exec, s[38:39]
	v_add_u32_e32 v64, v139, v140
	v_cvt_pk_bf16_f32 v5, v10, v11
	v_cvt_pk_bf16_f32 v0, v0, v1
	v_cvt_pk_bf16_f32 v1, v2, v3
	ds_write_b16 v168, v4 offset:9216
	ds_write_b16_d16_hi v168, v4 offset:13568
	ds_write_b16 v168, v5 offset:17920
	ds_write_b16_d16_hi v168, v5 offset:22272
	ds_write_b16 v168, v0 offset:26624
	ds_write_b16_d16_hi v168, v0 offset:30976
	ds_write_b16 v168, v1 offset:35328
	ds_write_b16_d16_hi v168, v1 offset:39680
	s_waitcnt lgkmcnt(0)
	s_barrier
	s_cbranch_vccnz .LBB0_605
	ds_read_b128 v[0:3], v64 offset:9216
	s_waitcnt lgkmcnt(0)
	v_mfma_f32_32x32x16_bf16 v[0:15], v[0:3], v[110:113], 0
	s_and_b64 vcc, exec, s[38:39]
	s_cbranch_vccnz .LBB0_577
